# P2 epilogue: rinv loads and the epilogue's weight/bias loads in flight together (one exposed round trip instead of two); coalesced mini-phase rinv pass
# baseline (speedup 1.0000x reference)
; __device__ __forceinline__ unsigned cvt_pk_bf16(float lo, float hi) { unsigned r; asm volatile("v_cvt_pk_bf16_f32 %0, %1, %2" : "=v"(r) : "v"(lo), "v"(hi)); return r; }
; __device__ __forceinline__ float bflo(unsigned w) { return __uint_as_float(w << 16); }
; __device__ __forceinline__ float bfhi(unsigned w) { return __uint_as_float(w & 0xffff0000u); }
; __device__ __forceinline__ void norm_phase(KP p, bool first, int nslab) {
;     ...
;         f32x4 v[4]; float s = 0.f;
;         if (first) { const f32x4* xr = (const f32x4*)src_row(p, m) + lane;
; #pragma unroll
;             for (int j = 0; j < 4; ++j) v[j] = __builtin_nontemporal_load(xr + 64 * j); }
;         else { const u32x2* xr = (const u32x2*)(X + (size_t)m * D) + lane;
; #pragma unroll
;             for (int j = 0; j < 4; ++j) { const u32x2 w = __builtin_nontemporal_load(xr + 64 * j); v[j] = (f32x4){bflo(w.x), bfhi(w.x), bflo(w.y), bfhi(w.y)}; } }
;         const bool fold = (!first) && m >= 64 * 256;
;         if (fold) { const f32x4* sl = (const f32x4*)(p->ws + WS_SLAB) + (size_t)(m - 64 * 256) * (D / 4) + lane;
;             for (int q = 0; q < nslab; ++q) {
; #pragma unroll
;                 for (int j = 0; j < 4; ++j) v[j] += sl[(size_t)q * 256 * (D / 4) + 64 * j]; } }
;         if (first || fold) { u32x2* xo = (u32x2*)(X + (size_t)m * D) + lane;
; #pragma unroll
;             for (int j = 0; j < 4; ++j) { u32x2 w; w.x = cvt_pk_bf16(v[j][0], v[j][1]); w.y = cvt_pk_bf16(v[j][2], v[j][3]); xo[64 * j] = w; } }
; #pragma unroll
;         for (int j = 0; j < 4; ++j) s += (v[j][0] * v[j][0] + v[j][1] * v[j][1]) + (v[j][2] * v[j][2] + v[j][3] * v[j][3]);
;         const float rinv = rsqrtf(wave_sum(s) * (1.f / D) + EPS);
.LBB0_59:
	s_waitcnt lgkmcnt(0)
	s_cmp_eq_u32 s56, 0
	s_cbranch_scc1 .Lp1_orig
	s_mov_b64 s[4:5], s[0:1]
	v_mov_b32_e32 v0, v209
	s_load_dwordx2 s[8:9], s[4:5], 0xe8
	v_and_b32_e32 v2, 63, v0
	v_readfirstlane_b32 s6, v0
	s_nop 3
	s_lshr_b32 s6, s6, 6
	s_waitcnt lgkmcnt(0)
	s_add_u32 s10, s8, 0x25c8000
	s_addc_u32 s11, s9, 0
	s_add_u32 s12, s8, 0x18c48000
	s_addc_u32 s13, s9, 0
	s_add_u32 s14, s8, 0x19068000
	s_addc_u32 s15, s9, 0
	s_cmpk_lt_u32 s2, 128
	s_cbranch_scc1 .Lnm_part2_p1
	s_cmpk_lt_u32 s2, 0xe0
	s_cbranch_scc1 .Lp1m_exit
	s_sub_i32 s16, s2, 0xe0
	s_lshl_b32 s16, s16, 3
	s_add_i32 s16, s16, s6
	s_add_i32 s18, s16, 0x4000
	s_lshl_b32 s19, s18, 2
	s_lshl_b32 s18, s18, 11
	s_add_u32 s10, s10, s18
	s_addc_u32 s11, s11, 0
	s_add_u32 s14, s14, s19
	s_addc_u32 s15, s15, 0
	v_lshlrev_b32_e32 v5, 3, v2
	v_lshlrev_b32_e32 v6, 4, v2
	global_load_dwordx2 v[18:19], v5, s[10:11]
	global_load_dwordx2 v[20:21], v5, s[10:11] offset:512
	global_load_dwordx2 v[22:23], v5, s[10:11] offset:1024
	global_load_dwordx2 v[24:25], v5, s[10:11] offset:1536
	s_lshl_b32 s18, s16, 12
	s_add_u32 s18, s8, s18
	s_addc_u32 s19, s9, 0
	s_add_u32 s18, s18, 0x1a3ac000
	s_addc_u32 s19, s19, 0
	global_load_dwordx4 v[32:35], v6, s[18:19]
	global_load_dwordx4 v[36:39], v6, s[18:19] offset:1024
	global_load_dwordx4 v[40:43], v6, s[18:19] offset:2048
	global_load_dwordx4 v[44:47], v6, s[18:19] offset:3072
	s_add_u32 s18, s18, 0x100000
	s_addc_u32 s19, s19, 0
	global_load_dwordx4 v[48:51], v6, s[18:19]
	global_load_dwordx4 v[52:55], v6, s[18:19] offset:1024
	global_load_dwordx4 v[56:59], v6, s[18:19] offset:2048
	global_load_dwordx4 v[60:63], v6, s[18:19] offset:3072
	s_add_u32 s18, s18, 0x100000
	s_addc_u32 s19, s19, 0
	global_load_dwordx4 v[64:67], v6, s[18:19]
	global_load_dwordx4 v[68:71], v6, s[18:19] offset:1024
	global_load_dwordx4 v[72:75], v6, s[18:19] offset:2048
	global_load_dwordx4 v[76:79], v6, s[18:19] offset:3072
	s_add_u32 s18, s18, 0x100000
	s_addc_u32 s19, s19, 0
	global_load_dwordx4 v[80:83], v6, s[18:19]
	global_load_dwordx4 v[84:87], v6, s[18:19] offset:1024
	global_load_dwordx4 v[88:91], v6, s[18:19] offset:2048
	global_load_dwordx4 v[92:95], v6, s[18:19] offset:3072
	s_add_u32 s18, s18, 0x100000
	s_addc_u32 s19, s19, 0
	global_load_dwordx4 v[96:99], v6, s[18:19]
	global_load_dwordx4 v[100:103], v6, s[18:19] offset:1024
	global_load_dwordx4 v[104:107], v6, s[18:19] offset:2048
	global_load_dwordx4 v[108:111], v6, s[18:19] offset:3072
	s_add_u32 s18, s18, 0x100000
	s_addc_u32 s19, s19, 0
	global_load_dwordx4 v[112:115], v6, s[18:19]
	global_load_dwordx4 v[116:119], v6, s[18:19] offset:1024
	global_load_dwordx4 v[120:123], v6, s[18:19] offset:2048
	global_load_dwordx4 v[124:127], v6, s[18:19] offset:3072
	s_add_u32 s18, s18, 0x100000
	s_addc_u32 s19, s19, 0
	global_load_dwordx4 v[128:131], v6, s[18:19]
	global_load_dwordx4 v[132:135], v6, s[18:19] offset:1024
	global_load_dwordx4 v[136:139], v6, s[18:19] offset:2048
	global_load_dwordx4 v[140:143], v6, s[18:19] offset:3072
	s_add_u32 s18, s18, 0x100000
	s_addc_u32 s19, s19, 0
	global_load_dwordx4 v[144:147], v6, s[18:19]
	global_load_dwordx4 v[148:151], v6, s[18:19] offset:1024
	global_load_dwordx4 v[152:155], v6, s[18:19] offset:2048
	global_load_dwordx4 v[156:159], v6, s[18:19] offset:3072
	s_add_u32 s18, s18, 0x100000
	s_addc_u32 s19, s19, 0
	s_waitcnt vmcnt(32)
	v_lshlrev_b32_e32 v224, 16, v18
	v_and_b32_e32 v225, 0xffff0000, v18
	v_lshlrev_b32_e32 v226, 16, v19
	v_and_b32_e32 v227, 0xffff0000, v19
	v_lshlrev_b32_e32 v228, 16, v20
	v_and_b32_e32 v229, 0xffff0000, v20
	v_lshlrev_b32_e32 v230, 16, v21
	v_and_b32_e32 v231, 0xffff0000, v21
	v_lshlrev_b32_e32 v232, 16, v22
	v_and_b32_e32 v233, 0xffff0000, v22
	v_lshlrev_b32_e32 v234, 16, v23
	v_and_b32_e32 v235, 0xffff0000, v23
	v_lshlrev_b32_e32 v236, 16, v24
	v_and_b32_e32 v237, 0xffff0000, v24
	v_lshlrev_b32_e32 v238, 16, v25
	v_and_b32_e32 v239, 0xffff0000, v25
	s_waitcnt vmcnt(28)
	v_add_f32_e32 v224, v224, v32
	v_add_f32_e32 v225, v225, v33
	v_add_f32_e32 v226, v226, v34
	v_add_f32_e32 v227, v227, v35
	v_add_f32_e32 v228, v228, v36
	v_add_f32_e32 v229, v229, v37
	v_add_f32_e32 v230, v230, v38
	v_add_f32_e32 v231, v231, v39
	v_add_f32_e32 v232, v232, v40
	v_add_f32_e32 v233, v233, v41
	v_add_f32_e32 v234, v234, v42
	v_add_f32_e32 v235, v235, v43
	v_add_f32_e32 v236, v236, v44
	v_add_f32_e32 v237, v237, v45
	v_add_f32_e32 v238, v238, v46
	v_add_f32_e32 v239, v239, v47
	s_waitcnt vmcnt(24)
	v_add_f32_e32 v224, v224, v48
	v_add_f32_e32 v225, v225, v49
	v_add_f32_e32 v226, v226, v50
	v_add_f32_e32 v227, v227, v51
	v_add_f32_e32 v228, v228, v52
	v_add_f32_e32 v229, v229, v53
	v_add_f32_e32 v230, v230, v54
	v_add_f32_e32 v231, v231, v55
	v_add_f32_e32 v232, v232, v56
	v_add_f32_e32 v233, v233, v57
	v_add_f32_e32 v234, v234, v58
	v_add_f32_e32 v235, v235, v59
	v_add_f32_e32 v236, v236, v60
	v_add_f32_e32 v237, v237, v61
	v_add_f32_e32 v238, v238, v62
	v_add_f32_e32 v239, v239, v63
	s_waitcnt vmcnt(20)
	v_add_f32_e32 v224, v224, v64
	v_add_f32_e32 v225, v225, v65
	v_add_f32_e32 v226, v226, v66
	v_add_f32_e32 v227, v227, v67
	v_add_f32_e32 v228, v228, v68
	v_add_f32_e32 v229, v229, v69
	v_add_f32_e32 v230, v230, v70
	v_add_f32_e32 v231, v231, v71
	v_add_f32_e32 v232, v232, v72
	v_add_f32_e32 v233, v233, v73
	v_add_f32_e32 v234, v234, v74
	v_add_f32_e32 v235, v235, v75
	v_add_f32_e32 v236, v236, v76
	v_add_f32_e32 v237, v237, v77
	v_add_f32_e32 v238, v238, v78
	v_add_f32_e32 v239, v239, v79
	s_waitcnt vmcnt(16)
; __device__ __forceinline__ unsigned cvt_pk_bf16(float lo, float hi) { unsigned r; asm volatile("v_cvt_pk_bf16_f32 %0, %1, %2" : "=v"(r) : "v"(lo), "v"(hi)); return r; }
; __device__ __forceinline__ void norm_phase(KP p, bool first, int nslab) {
;     ...
;         if (fold) { const f32x4* sl = (const f32x4*)(p->ws + WS_SLAB) + (size_t)(m - 64 * 256) * (D / 4) + lane;
;             for (int q = 0; q < nslab; ++q) {
; #pragma unroll
;                 for (int j = 0; j < 4; ++j) v[j] += sl[(size_t)q * 256 * (D / 4) + 64 * j]; } }
;         if (first || fold) { u32x2* xo = (u32x2*)(X + (size_t)m * D) + lane;
; #pragma unroll
;             for (int j = 0; j < 4; ++j) { u32x2 w; w.x = cvt_pk_bf16(v[j][0], v[j][1]); w.y = cvt_pk_bf16(v[j][2], v[j][3]); xo[64 * j] = w; } }
; #pragma unroll
;         for (int j = 0; j < 4; ++j) s += (v[j][0] * v[j][0] + v[j][1] * v[j][1]) + (v[j][2] * v[j][2] + v[j][3] * v[j][3]);
;         const float rinv = rsqrtf(wave_sum(s) * (1.f / D) + EPS);
	v_add_f32_e32 v224, v224, v80
	v_add_f32_e32 v225, v225, v81
	v_add_f32_e32 v226, v226, v82
	v_add_f32_e32 v227, v227, v83
	v_add_f32_e32 v228, v228, v84
	v_add_f32_e32 v229, v229, v85
	v_add_f32_e32 v230, v230, v86
	v_add_f32_e32 v231, v231, v87
	v_add_f32_e32 v232, v232, v88
	v_add_f32_e32 v233, v233, v89
	v_add_f32_e32 v234, v234, v90
	v_add_f32_e32 v235, v235, v91
	v_add_f32_e32 v236, v236, v92
	v_add_f32_e32 v237, v237, v93
	v_add_f32_e32 v238, v238, v94
	v_add_f32_e32 v239, v239, v95
	s_waitcnt vmcnt(12)
	v_add_f32_e32 v224, v224, v96
	v_add_f32_e32 v225, v225, v97
	v_add_f32_e32 v226, v226, v98
	v_add_f32_e32 v227, v227, v99
	v_add_f32_e32 v228, v228, v100
	v_add_f32_e32 v229, v229, v101
	v_add_f32_e32 v230, v230, v102
	v_add_f32_e32 v231, v231, v103
	v_add_f32_e32 v232, v232, v104
	v_add_f32_e32 v233, v233, v105
	v_add_f32_e32 v234, v234, v106
	v_add_f32_e32 v235, v235, v107
	v_add_f32_e32 v236, v236, v108
	v_add_f32_e32 v237, v237, v109
	v_add_f32_e32 v238, v238, v110
	v_add_f32_e32 v239, v239, v111
	s_waitcnt vmcnt(8)
	v_add_f32_e32 v224, v224, v112
	v_add_f32_e32 v225, v225, v113
	v_add_f32_e32 v226, v226, v114
	v_add_f32_e32 v227, v227, v115
	v_add_f32_e32 v228, v228, v116
	v_add_f32_e32 v229, v229, v117
	v_add_f32_e32 v230, v230, v118
	v_add_f32_e32 v231, v231, v119
	v_add_f32_e32 v232, v232, v120
	v_add_f32_e32 v233, v233, v121
	v_add_f32_e32 v234, v234, v122
	v_add_f32_e32 v235, v235, v123
	v_add_f32_e32 v236, v236, v124
	v_add_f32_e32 v237, v237, v125
	v_add_f32_e32 v238, v238, v126
	v_add_f32_e32 v239, v239, v127
	s_waitcnt vmcnt(4)
	v_add_f32_e32 v224, v224, v128
	v_add_f32_e32 v225, v225, v129
	v_add_f32_e32 v226, v226, v130
	v_add_f32_e32 v227, v227, v131
	v_add_f32_e32 v228, v228, v132
	v_add_f32_e32 v229, v229, v133
	v_add_f32_e32 v230, v230, v134
	v_add_f32_e32 v231, v231, v135
	v_add_f32_e32 v232, v232, v136
	v_add_f32_e32 v233, v233, v137
	v_add_f32_e32 v234, v234, v138
	v_add_f32_e32 v235, v235, v139
	v_add_f32_e32 v236, v236, v140
	v_add_f32_e32 v237, v237, v141
	v_add_f32_e32 v238, v238, v142
	v_add_f32_e32 v239, v239, v143
	s_waitcnt vmcnt(0)
	v_add_f32_e32 v224, v224, v144
	v_add_f32_e32 v225, v225, v145
	v_add_f32_e32 v226, v226, v146
	v_add_f32_e32 v227, v227, v147
	v_add_f32_e32 v228, v228, v148
	v_add_f32_e32 v229, v229, v149
	v_add_f32_e32 v230, v230, v150
	v_add_f32_e32 v231, v231, v151
	v_add_f32_e32 v232, v232, v152
	v_add_f32_e32 v233, v233, v153
	v_add_f32_e32 v234, v234, v154
	v_add_f32_e32 v235, v235, v155
	v_add_f32_e32 v236, v236, v156
	v_add_f32_e32 v237, v237, v157
	v_add_f32_e32 v238, v238, v158
	v_add_f32_e32 v239, v239, v159
	global_load_dwordx4 v[32:35], v6, s[18:19]
	global_load_dwordx4 v[36:39], v6, s[18:19] offset:1024
	global_load_dwordx4 v[40:43], v6, s[18:19] offset:2048
	global_load_dwordx4 v[44:47], v6, s[18:19] offset:3072
	s_add_u32 s18, s18, 0x100000
	s_addc_u32 s19, s19, 0
	global_load_dwordx4 v[48:51], v6, s[18:19]
	global_load_dwordx4 v[52:55], v6, s[18:19] offset:1024
	global_load_dwordx4 v[56:59], v6, s[18:19] offset:2048
	global_load_dwordx4 v[60:63], v6, s[18:19] offset:3072
	s_add_u32 s18, s18, 0x100000
	s_addc_u32 s19, s19, 0
	global_load_dwordx4 v[64:67], v6, s[18:19]
	global_load_dwordx4 v[68:71], v6, s[18:19] offset:1024
	global_load_dwordx4 v[72:75], v6, s[18:19] offset:2048
	global_load_dwordx4 v[76:79], v6, s[18:19] offset:3072
	s_add_u32 s18, s18, 0x100000
	s_addc_u32 s19, s19, 0
	s_waitcnt vmcnt(8)
	v_add_f32_e32 v224, v224, v32
	v_add_f32_e32 v225, v225, v33
	v_add_f32_e32 v226, v226, v34
	v_add_f32_e32 v227, v227, v35
	v_add_f32_e32 v228, v228, v36
	v_add_f32_e32 v229, v229, v37
	v_add_f32_e32 v230, v230, v38
	v_add_f32_e32 v231, v231, v39
	v_add_f32_e32 v232, v232, v40
	v_add_f32_e32 v233, v233, v41
	v_add_f32_e32 v234, v234, v42
	v_add_f32_e32 v235, v235, v43
	v_add_f32_e32 v236, v236, v44
	v_add_f32_e32 v237, v237, v45
	v_add_f32_e32 v238, v238, v46
	v_add_f32_e32 v239, v239, v47
	s_waitcnt vmcnt(4)
	v_add_f32_e32 v224, v224, v48
	v_add_f32_e32 v225, v225, v49
	v_add_f32_e32 v226, v226, v50
	v_add_f32_e32 v227, v227, v51
	v_add_f32_e32 v228, v228, v52
	v_add_f32_e32 v229, v229, v53
	v_add_f32_e32 v230, v230, v54
	v_add_f32_e32 v231, v231, v55
	v_add_f32_e32 v232, v232, v56
	v_add_f32_e32 v233, v233, v57
	v_add_f32_e32 v234, v234, v58
	v_add_f32_e32 v235, v235, v59
	v_add_f32_e32 v236, v236, v60
	v_add_f32_e32 v237, v237, v61
	v_add_f32_e32 v238, v238, v62
	v_add_f32_e32 v239, v239, v63
	s_waitcnt vmcnt(0)
	v_add_f32_e32 v224, v224, v64
	v_add_f32_e32 v225, v225, v65
	v_add_f32_e32 v226, v226, v66
	v_add_f32_e32 v227, v227, v67
	v_add_f32_e32 v228, v228, v68
	v_add_f32_e32 v229, v229, v69
	v_add_f32_e32 v230, v230, v70
	v_add_f32_e32 v231, v231, v71
	v_add_f32_e32 v232, v232, v72
	v_add_f32_e32 v233, v233, v73
	v_add_f32_e32 v234, v234, v74
	v_add_f32_e32 v235, v235, v75
	v_add_f32_e32 v236, v236, v76
	v_add_f32_e32 v237, v237, v77
	v_add_f32_e32 v238, v238, v78
	v_add_f32_e32 v239, v239, v79
	v_cvt_pk_bf16_f32 v26, v224, v225
	v_cvt_pk_bf16_f32 v27, v226, v227
	global_store_dwordx2 v5, v[26:27], s[10:11] sc0 sc1
	v_cvt_pk_bf16_f32 v28, v228, v229
	v_cvt_pk_bf16_f32 v29, v230, v231
	global_store_dwordx2 v5, v[28:29], s[10:11] offset:512 sc0 sc1
	v_cvt_pk_bf16_f32 v30, v232, v233
	v_cvt_pk_bf16_f32 v31, v234, v235
	global_store_dwordx2 v5, v[30:31], s[10:11] offset:1024 sc0 sc1
	v_cvt_pk_bf16_f32 v32, v236, v237
	v_cvt_pk_bf16_f32 v33, v238, v239
	global_store_dwordx2 v5, v[32:33], s[10:11] offset:1536 sc0 sc1
	v_mul_f32_e32 v7, v224, v224
	v_fmac_f32_e32 v7, v225, v225
	v_fmac_f32_e32 v7, v226, v226
	v_fmac_f32_e32 v7, v227, v227
	v_fmac_f32_e32 v7, v228, v228
	v_fmac_f32_e32 v7, v229, v229
	v_fmac_f32_e32 v7, v230, v230
	v_fmac_f32_e32 v7, v231, v231
	v_fmac_f32_e32 v7, v232, v232
	v_fmac_f32_e32 v7, v233, v233
	v_fmac_f32_e32 v7, v234, v234
	v_fmac_f32_e32 v7, v235, v235
	v_fmac_f32_e32 v7, v236, v236
	v_fmac_f32_e32 v7, v237, v237
	v_fmac_f32_e32 v7, v238, v238
	v_fmac_f32_e32 v7, v239, v239
	v_xor_b32_e32 v10, 1, v2
	v_lshlrev_b32_e32 v10, 2, v10
	ds_bpermute_b32 v10, v10, v7
	s_waitcnt lgkmcnt(0)
	v_add_f32_e32 v7, v7, v10
	v_xor_b32_e32 v10, 2, v2
	v_lshlrev_b32_e32 v10, 2, v10
	ds_bpermute_b32 v10, v10, v7
	s_waitcnt lgkmcnt(0)
	v_add_f32_e32 v7, v7, v10
	v_xor_b32_e32 v10, 4, v2
	v_lshlrev_b32_e32 v10, 2, v10
	ds_bpermute_b32 v10, v10, v7
	s_waitcnt lgkmcnt(0)
	v_add_f32_e32 v7, v7, v10
	v_xor_b32_e32 v10, 8, v2
	v_lshlrev_b32_e32 v10, 2, v10
	ds_bpermute_b32 v10, v10, v7
	s_waitcnt lgkmcnt(0)
	v_add_f32_e32 v7, v7, v10
	v_xor_b32_e32 v10, 16, v2
	v_lshlrev_b32_e32 v10, 2, v10
	ds_bpermute_b32 v10, v10, v7
	s_waitcnt lgkmcnt(0)
	v_add_f32_e32 v7, v7, v10
	v_xor_b32_e32 v10, 32, v2
	v_lshlrev_b32_e32 v10, 2, v10
	ds_bpermute_b32 v10, v10, v7
	s_waitcnt lgkmcnt(0)
	v_add_f32_e32 v7, v7, v10
	v_fmamk_f32 v7, v7, 0x3a800000, v213
	v_rsq_f32_e32 v7, v7
	s_nop 0
	global_store_dword v1, v7, s[14:15] sc0 sc1
	s_branch .Lp1m_exit
; __device__ __forceinline__ void norm_phase(KP p, bool first, int nslab) {
;     ...
;         for (int j = 0; j < 4; ++j) s += (v[j][0] * v[j][0] + v[j][1] * v[j][1]) + (v[j][2] * v[j][2] + v[j][3] * v[j][3]);
;         const float rinv = rsqrtf(wave_sum(s) * (1.f / D) + EPS);
.Lnm_part2_p1:
	s_lshl_b32 s16, s2, 3
	s_add_i32 s16, s16, s6
	s_lshl_b32 s18, s16, 12
	s_add_u32 s12, s12, s18
	s_addc_u32 s13, s13, 0
	v_lshlrev_b32_e32 v6, 4, v2
	global_load_dwordx4 v[32:35], v6, s[12:13]
	global_load_dwordx4 v[36:39], v6, s[12:13] offset:1024
	global_load_dwordx4 v[40:43], v6, s[12:13] offset:2048
	global_load_dwordx4 v[44:47], v6, s[12:13] offset:3072
	s_lshl_b32 s18, s16, 6
	s_add_u32 s14, s14, s18
	s_addc_u32 s15, s15, 0
	v_lshrrev_b32_e32 v10, 4, v2
	v_lshlrev_b32_e32 v10, 2, v10
	s_waitcnt vmcnt(3)
	v_add_f32_e32 v48, v32, v33
	v_add_f32_e32 v34, v34, v35
	v_add_f32_e32 v48, v48, v34
	s_waitcnt vmcnt(2)
	v_add_f32_e32 v49, v36, v37
	v_add_f32_e32 v38, v38, v39
	v_add_f32_e32 v49, v49, v38
	s_waitcnt vmcnt(1)
	v_add_f32_e32 v50, v40, v41
	v_add_f32_e32 v42, v42, v43
	v_add_f32_e32 v50, v50, v42
	s_waitcnt vmcnt(0)
	v_add_f32_e32 v51, v44, v45
	v_add_f32_e32 v46, v46, v47
	v_add_f32_e32 v51, v51, v46
	s_nop 1
	v_add_f32_dpp v52, v48, v48 quad_perm:[1,0,3,2] row_mask:0xf bank_mask:0xf
	v_add_f32_dpp v53, v49, v49 quad_perm:[1,0,3,2] row_mask:0xf bank_mask:0xf
	v_add_f32_dpp v54, v50, v50 quad_perm:[1,0,3,2] row_mask:0xf bank_mask:0xf
	v_add_f32_dpp v55, v51, v51 quad_perm:[1,0,3,2] row_mask:0xf bank_mask:0xf
	s_nop 1
	v_mov_b32_e32 v48, v52
	v_mov_b32_e32 v49, v53
	v_mov_b32_e32 v50, v54
	v_mov_b32_e32 v51, v55
	s_nop 1
	v_add_f32_dpp v52, v48, v48 quad_perm:[2,3,0,1] row_mask:0xf bank_mask:0xf
	v_add_f32_dpp v53, v49, v49 quad_perm:[2,3,0,1] row_mask:0xf bank_mask:0xf
	v_add_f32_dpp v54, v50, v50 quad_perm:[2,3,0,1] row_mask:0xf bank_mask:0xf
	v_add_f32_dpp v55, v51, v51 quad_perm:[2,3,0,1] row_mask:0xf bank_mask:0xf
	s_nop 1
	v_mov_b32_e32 v48, v52
	v_mov_b32_e32 v49, v53
	v_mov_b32_e32 v50, v54
	v_mov_b32_e32 v51, v55
	s_nop 1
	v_add_f32_dpp v52, v48, v48 row_half_mirror row_mask:0xf bank_mask:0xf
	v_add_f32_dpp v53, v49, v49 row_half_mirror row_mask:0xf bank_mask:0xf
	v_add_f32_dpp v54, v50, v50 row_half_mirror row_mask:0xf bank_mask:0xf
	v_add_f32_dpp v55, v51, v51 row_half_mirror row_mask:0xf bank_mask:0xf
	s_nop 1
	v_mov_b32_e32 v48, v52
	v_mov_b32_e32 v49, v53
	v_mov_b32_e32 v50, v54
	v_mov_b32_e32 v51, v55
	s_nop 1
	v_add_f32_dpp v52, v48, v48 row_mirror row_mask:0xf bank_mask:0xf
	v_add_f32_dpp v53, v49, v49 row_mirror row_mask:0xf bank_mask:0xf
	v_add_f32_dpp v54, v50, v50 row_mirror row_mask:0xf bank_mask:0xf
	v_add_f32_dpp v55, v51, v51 row_mirror row_mask:0xf bank_mask:0xf
	s_nop 1
	v_mov_b32_e32 v48, v52
	v_mov_b32_e32 v49, v53
	v_mov_b32_e32 v50, v54
	v_mov_b32_e32 v51, v55
	v_fmamk_f32 v48, v48, 0x3a800000, v213
	v_fmamk_f32 v49, v49, 0x3a800000, v213
	v_fmamk_f32 v50, v50, 0x3a800000, v213
	v_fmamk_f32 v51, v51, 0x3a800000, v213
	v_rsq_f32_e32 v48, v48
	v_rsq_f32_e32 v49, v49
	v_rsq_f32_e32 v50, v50
	v_rsq_f32_e32 v51, v51
	s_mov_b64 s[18:19], exec
	s_mov_b32 exec_lo, 0x10001
	s_mov_b32 exec_hi, 0x10001
	global_store_dword v10, v48, s[14:15] sc0 sc1
	global_store_dword v10, v49, s[14:15] offset:16 sc0 sc1
	global_store_dword v10, v50, s[14:15] offset:32 sc0 sc1
	global_store_dword v10, v51, s[14:15] offset:48 sc0 sc1
	s_mov_b64 exec, s[18:19]

; __device__ __forceinline__ unsigned cvt_pk_bf16(float lo, float hi) { unsigned r; asm volatile("v_cvt_pk_bf16_f32 %0, %1, %2" : "=v"(r) : "v"(lo), "v"(hi)); return r; }
;     __device__ __forceinline__ void operator()(const f32x4 (&acc)[2][2][4][2], const Unit& u, int wr, int wc, int fr, int fq) const {
;         const int rbase = u.pm * BM + wr * 64 + fr;
;         if (u.pn >= 16) {
;             const int col0 = u.pn * BM + wc * 32 + 8 * fq;
;             f32x4 bv[2][2];
; #pragma unroll
;             for (int bj = 0; bj < 2; ++bj)
; #pragma unroll
;                 for (int n = 0; n < 2; ++n) bv[bj][n] = *(const f32x4*)(bias + col0 + bj * HALF + 4 * n);
; #pragma unroll
;             for (int ai = 0; ai < 2; ++ai)
; #pragma unroll
;                 for (int m = 0; m < 4; ++m) { bf16_t* rowp = O + (size_t)(rbase + ai * HALF + m * 16) * DP + (col0 - 2048);
; #pragma unroll
;                     for (int bj = 0; bj < 2; ++bj) { const f32x4 v0 = acc[ai][bj][m][0] + bv[bj][0], v1 = acc[ai][bj][m][1] + bv[bj][1];
;                         u32x4 w; w.x = cvt_pk_bf16(v0[0], v0[1]); w.y = cvt_pk_bf16(v0[2], v0[3]); w.z = cvt_pk_bf16(v1[0], v1[1]); w.w = cvt_pk_bf16(v1[2], v1[3]);
;                         *(u32x4*)(rowp + bj * HALF) = w; } }
;             return;
;         }
;         const int xch = u.pn * 64 + wc * 16 + 4 * fq;
;         const f32x4 w0 = *(const f32x4*)(cw + xch), w1 = *(const f32x4*)(cw + D + xch), w2 = *(const f32x4*)(cw + 2 * D + xch);
;         const f32x4 bm = *(const f32x4*)(bias + u.pn * BM + HALF + wc * 32 + 8 * fq + 4);
.LBB0_164:
	s_cmp_lg_u32 s48, 0
	s_cbranch_scc1 .Lfw_p2_done
	s_cmp_eq_u32 s56, 0
	s_cbranch_scc1 .Lfw_p2_done
	s_lshl_b32 s14, s56, 4
	s_add_u32 s12, s64, 0x13ce3e00
	s_addc_u32 s13, s65, 0
	s_add_u32 s12, s12, s14
	s_addc_u32 s13, s13, 0
	v_mov_b32_e32 v195, 0
	s_mov_b32 s14, 0
.Lfw_p2_loop:
	global_load_dword v196, v195, s[12:13] sc0 sc1
	s_waitcnt vmcnt(0)
	v_readfirstlane_b32 s15, v196
	s_nop 3
	s_cmpk_ge_u32 s15, 0x100
	s_cbranch_scc1 .Lfw_p2_done
	s_sleep 1
	s_add_i32 s14, s14, 1
	s_cmp_lt_u32 s14, 0x100000
	s_cbranch_scc1 .Lfw_p2_loop
.Lfw_p2_done:
	s_lshl_b32 s14, s96, 8
	s_add_i32 s14, s14, s42
	s_lshl_b32 s14, s14, 2
	s_add_u32 s12, s64, 0x129a0000
	s_addc_u32 s13, s65, 0
	s_add_u32 s12, s12, s14
	s_addc_u32 s13, s13, 0
	v_lshlrev_b32_e32 v195, 2, v184
	global_load_dword v196, v195, s[12:13]
	global_load_dword v197, v195, s[12:13] offset:64
	global_load_dword v198, v195, s[12:13] offset:128
	global_load_dword v199, v195, s[12:13] offset:192
	global_load_dword v200, v195, s[12:13] offset:512
	global_load_dword v201, v195, s[12:13] offset:576
	global_load_dword v202, v195, s[12:13] offset:640
	global_load_dword v203, v195, s[12:13] offset:704
	s_lshl_b32 s14, s96, 8
	s_add_i32 s55, s14, s42
	v_or_b32_e32 v190, s55, v184
	s_cmp_lt_i32 s94, 16
	s_cbranch_scc0 .Lp2r_hi
	v_lshl_or_b32 v176, s94, 6, v186
	v_ashrrev_i32_e32 v177, 31, v176
	v_lshlrev_b64 v[178:179], 2, v[176:177]
	v_lshl_add_u64 v[130:131], s[72:73], 0, v[178:179]
	s_lshl_b32 s12, s94, 8
	v_lshl_add_u64 v[132:133], s[82:83], 0, v[178:179]
	global_load_dwordx4 v[134:137], v[130:131], off
	global_load_dwordx4 v[142:145], v[132:133], off
	v_lshl_add_u64 v[130:131], s[84:85], 0, v[178:179]
	s_ashr_i32 s13, s12, 31
	global_load_dwordx4 v[138:141], v[130:131], off
	v_lshl_add_u64 v[130:131], s[12:13], 2, v[170:171]
	global_load_dwordx4 v[130:133], v[130:131], off offset:528
	s_waitcnt vmcnt(4)
	v_mul_f32_e32 v126, v196, v126
	v_mul_f32_e32 v127, v196, v127
	v_mul_f32_e32 v128, v196, v128
	v_mul_f32_e32 v129, v196, v129
	v_mul_f32_e32 v122, v196, v122
	v_mul_f32_e32 v123, v196, v123
	v_mul_f32_e32 v124, v196, v124
	v_mul_f32_e32 v125, v196, v125
	v_mul_f32_e32 v118, v196, v118
	v_mul_f32_e32 v119, v196, v119
	v_mul_f32_e32 v120, v196, v120
	v_mul_f32_e32 v121, v196, v121
	v_mul_f32_e32 v114, v196, v114
	v_mul_f32_e32 v115, v196, v115
	v_mul_f32_e32 v116, v196, v116
	v_mul_f32_e32 v117, v196, v117
	v_mul_f32_e32 v110, v197, v110
	v_mul_f32_e32 v111, v197, v111
	v_mul_f32_e32 v112, v197, v112
	v_mul_f32_e32 v113, v197, v113
	v_mul_f32_e32 v106, v197, v106
	v_mul_f32_e32 v107, v197, v107
	v_mul_f32_e32 v108, v197, v108
	v_mul_f32_e32 v109, v197, v109
	v_mul_f32_e32 v102, v197, v102
	v_mul_f32_e32 v103, v197, v103
	v_mul_f32_e32 v104, v197, v104
	v_mul_f32_e32 v105, v197, v105
	v_mul_f32_e32 v98, v197, v98
	v_mul_f32_e32 v99, v197, v99
	v_mul_f32_e32 v100, v197, v100
	v_mul_f32_e32 v101, v197, v101
	v_mul_f32_e32 v94, v198, v94
	v_mul_f32_e32 v95, v198, v95
	v_mul_f32_e32 v96, v198, v96
	v_mul_f32_e32 v97, v198, v97
	v_mul_f32_e32 v90, v198, v90
	v_mul_f32_e32 v91, v198, v91
	v_mul_f32_e32 v92, v198, v92
	v_mul_f32_e32 v93, v198, v93
	v_mul_f32_e32 v86, v198, v86
	v_mul_f32_e32 v87, v198, v87
	v_mul_f32_e32 v88, v198, v88
	v_mul_f32_e32 v89, v198, v89
	v_mul_f32_e32 v82, v198, v82
	v_mul_f32_e32 v83, v198, v83
	v_mul_f32_e32 v84, v198, v84
	v_mul_f32_e32 v85, v198, v85
	v_mul_f32_e32 v78, v199, v78
	v_mul_f32_e32 v79, v199, v79
	v_mul_f32_e32 v80, v199, v80
	v_mul_f32_e32 v81, v199, v81
	v_mul_f32_e32 v74, v199, v74
	v_mul_f32_e32 v75, v199, v75
	v_mul_f32_e32 v76, v199, v76
	v_mul_f32_e32 v77, v199, v77
	v_mul_f32_e32 v70, v199, v70
	v_mul_f32_e32 v71, v199, v71
	v_mul_f32_e32 v72, v199, v72
	v_mul_f32_e32 v73, v199, v73
	v_mul_f32_e32 v66, v199, v66
	v_mul_f32_e32 v67, v199, v67
	v_mul_f32_e32 v68, v199, v68
	v_mul_f32_e32 v69, v199, v69
	v_mul_f32_e32 v62, v200, v62
	v_mul_f32_e32 v63, v200, v63
	v_mul_f32_e32 v64, v200, v64
	v_mul_f32_e32 v65, v200, v65
	v_mul_f32_e32 v58, v200, v58
	v_mul_f32_e32 v59, v200, v59
	v_mul_f32_e32 v60, v200, v60
	v_mul_f32_e32 v61, v200, v61
	v_mul_f32_e32 v54, v200, v54
	v_mul_f32_e32 v55, v200, v55
	v_mul_f32_e32 v56, v200, v56
	v_mul_f32_e32 v57, v200, v57
	v_mul_f32_e32 v46, v200, v46
	v_mul_f32_e32 v47, v200, v47
	v_mul_f32_e32 v48, v200, v48
	v_mul_f32_e32 v49, v200, v49
	v_mul_f32_e32 v50, v201, v50
	v_mul_f32_e32 v51, v201, v51
	v_mul_f32_e32 v52, v201, v52
	v_mul_f32_e32 v53, v201, v53
	v_mul_f32_e32 v42, v201, v42
	v_mul_f32_e32 v43, v201, v43
	v_mul_f32_e32 v44, v201, v44
	v_mul_f32_e32 v45, v201, v45
	v_mul_f32_e32 v38, v201, v38
	v_mul_f32_e32 v39, v201, v39
	v_mul_f32_e32 v40, v201, v40
	v_mul_f32_e32 v41, v201, v41
	v_mul_f32_e32 v30, v201, v30
	v_mul_f32_e32 v31, v201, v31
	v_mul_f32_e32 v32, v201, v32
	v_mul_f32_e32 v33, v201, v33
	v_mul_f32_e32 v34, v202, v34
	v_mul_f32_e32 v35, v202, v35
	v_mul_f32_e32 v36, v202, v36
	v_mul_f32_e32 v37, v202, v37
	v_mul_f32_e32 v26, v202, v26
	v_mul_f32_e32 v27, v202, v27
	v_mul_f32_e32 v28, v202, v28
	v_mul_f32_e32 v29, v202, v29
	v_mul_f32_e32 v22, v202, v22
	v_mul_f32_e32 v23, v202, v23
	v_mul_f32_e32 v24, v202, v24
	v_mul_f32_e32 v25, v202, v25
	v_mul_f32_e32 v14, v202, v14
	v_mul_f32_e32 v15, v202, v15
	v_mul_f32_e32 v16, v202, v16
	v_mul_f32_e32 v17, v202, v17
	v_mul_f32_e32 v18, v203, v18
	v_mul_f32_e32 v19, v203, v19
	v_mul_f32_e32 v20, v203, v20
	v_mul_f32_e32 v21, v203, v21
	v_mul_f32_e32 v10, v203, v10
	v_mul_f32_e32 v11, v203, v11
	v_mul_f32_e32 v12, v203, v12
	v_mul_f32_e32 v13, v203, v13
	v_mul_f32_e32 v6, v203, v6
	v_mul_f32_e32 v7, v203, v7
	v_mul_f32_e32 v8, v203, v8
	v_mul_f32_e32 v9, v203, v9
	v_mul_f32_e32 v2, v203, v2
	v_mul_f32_e32 v3, v203, v3
	v_mul_f32_e32 v4, v203, v4
	v_mul_f32_e32 v5, v203, v5
	s_branch .Lp2r_lo_cont
;     __device__ __forceinline__ void operator()(const f32x4 (&acc)[2][2][4][2], const Unit& u, int wr, int wc, int fr, int fq) const {
;     ...
;         const int xch = u.pn * 64 + wc * 16 + 4 * fq;
;         const f32x4 w0 = *(const f32x4*)(cw + xch), w1 = *(const f32x4*)(cw + D + xch), w2 = *(const f32x4*)(cw + 2 * D + xch);
;         const f32x4 bm = *(const f32x4*)(bias + u.pn * BM + HALF + wc * 32 + 8 * fq + 4);
;         const int b0 = (u.pm * BM) / TP, rb = (b0 + 1) * TP;
; #pragma unroll
;         for (int ai = 0; ai < 2; ++ai) {
;             f32x4 z[4];
; #pragma unroll
;             for (int m = 0; m < 4; ++m) z[m] = acc[ai][0][m][1] * acc[ai][1][m][0];
;             if (u.pm == 64 && ai == 1) {
; #pragma unroll
;                 for (int m = 0; m < 4; ++m) { const int r = rbase + HALF + 16 * m, sb = r - MP;
;                     const f32x4 z2 = *(const f32x4*)(st + (size_t)(sb * 2) * D + xch), z1 = *(const f32x4*)(st + (size_t)(sb * 2 + 1) * D + xch);
;                     const f32x4 ua = acc[1][0][m][0] * (w0 * z2 + w1 * z1 + w2 * z[m]), ma = acc[1][1][m][1] + bm;
;                     bf16_t* rowp = O + (size_t)r * DP + xch;
;                     u32x2 a; a.x = cvt_pk_bf16(ua[0], ua[1]); a.y = cvt_pk_bf16(ua[2], ua[3]); *(u32x2*)(rowp + C_UA) = a;
;                     u32x2 g; g.x = cvt_pk_bf16(ma[0], ma[1]); g.y = cvt_pk_bf16(ma[2], ma[3]); *(u32x2*)(rowp + C_MA) = g;
;                     *(f32x4*)(outs + (size_t)(sb * 2) * D + xch) = z1; *(f32x4*)(outs + (size_t)(sb * 2 + 1) * D + xch) = z[m]; }
;             } else {
; #pragma unroll
;                 for (int m = 0; m < 4; ++m) { const int r = rbase + ai * HALF + 16 * m; const bool hi = r >= rb; const int t = hi ? r - rb : r - b0 * TP, b = hi ? b0 + 1 : b0;
;                     f32x4 z1, z2;
; #pragma unroll
;                     for (int e = 0; e < 4; ++e) { float a1 = dpp_ror1(z[m][e]), a2 = dpp_ror2(z[m][e]);
;                         if (m > 0) { const float xp = z[m > 0 ? m - 1 : 0][e]; const float p1 = dpp_ror1(xp), p2 = dpp_ror2(xp); a1 = fr >= 1 ? a1 : p1; a2 = fr >= 2 ? a2 : p2; }
;                         if (t == 0) a1 = 0.f; if (t <= 1) a2 = 0.f; z1[e] = a1; z2[e] = a2; }
;                     const f32x4 gb = acc[ai][0][m][0], ua = gb * (w0 * z2 + w1 * z1 + w2 * z[m]), ma = acc[ai][1][m][1] + bm;
;                     bf16_t* rowp = O + (size_t)r * DP + xch;
.Lp2r_hi:
	v_lshl_or_b32 v0, s94, 8, v188
	v_lshl_add_u64 v[134:135], v[0:1], 2, s[66:67]
	global_load_dwordx4 v[138:141], v[134:135], off offset:16
	global_load_dwordx4 v[142:145], v[134:135], off
	global_load_dwordx4 v[130:133], v[134:135], off offset:528
	s_nop 0
	global_load_dwordx4 v[134:137], v[134:135], off offset:512
	s_waitcnt vmcnt(4)
	v_mul_f32_e32 v126, v196, v126
	v_mul_f32_e32 v127, v196, v127
	v_mul_f32_e32 v128, v196, v128
	v_mul_f32_e32 v129, v196, v129
	v_mul_f32_e32 v122, v196, v122
	v_mul_f32_e32 v123, v196, v123
	v_mul_f32_e32 v124, v196, v124
	v_mul_f32_e32 v125, v196, v125
	v_mul_f32_e32 v118, v196, v118
	v_mul_f32_e32 v119, v196, v119
	v_mul_f32_e32 v120, v196, v120
	v_mul_f32_e32 v121, v196, v121
	v_mul_f32_e32 v114, v196, v114
	v_mul_f32_e32 v115, v196, v115
	v_mul_f32_e32 v116, v196, v116
	v_mul_f32_e32 v117, v196, v117
	v_mul_f32_e32 v110, v197, v110
	v_mul_f32_e32 v111, v197, v111
	v_mul_f32_e32 v112, v197, v112
	v_mul_f32_e32 v113, v197, v113
	v_mul_f32_e32 v106, v197, v106
	v_mul_f32_e32 v107, v197, v107
	v_mul_f32_e32 v108, v197, v108
	v_mul_f32_e32 v109, v197, v109
	v_mul_f32_e32 v102, v197, v102
	v_mul_f32_e32 v103, v197, v103
	v_mul_f32_e32 v104, v197, v104
	v_mul_f32_e32 v105, v197, v105
	v_mul_f32_e32 v98, v197, v98
	v_mul_f32_e32 v99, v197, v99
	v_mul_f32_e32 v100, v197, v100
	v_mul_f32_e32 v101, v197, v101
	v_mul_f32_e32 v94, v198, v94
	v_mul_f32_e32 v95, v198, v95
	v_mul_f32_e32 v96, v198, v96
	v_mul_f32_e32 v97, v198, v97
	v_mul_f32_e32 v90, v198, v90
	v_mul_f32_e32 v91, v198, v91
	v_mul_f32_e32 v92, v198, v92
	v_mul_f32_e32 v93, v198, v93
	v_mul_f32_e32 v86, v198, v86
	v_mul_f32_e32 v87, v198, v87
	v_mul_f32_e32 v88, v198, v88
	v_mul_f32_e32 v89, v198, v89
	v_mul_f32_e32 v82, v198, v82
	v_mul_f32_e32 v83, v198, v83
	v_mul_f32_e32 v84, v198, v84
	v_mul_f32_e32 v85, v198, v85
	v_mul_f32_e32 v78, v199, v78
	v_mul_f32_e32 v79, v199, v79
	v_mul_f32_e32 v80, v199, v80
	v_mul_f32_e32 v81, v199, v81
	v_mul_f32_e32 v74, v199, v74
	v_mul_f32_e32 v75, v199, v75
	v_mul_f32_e32 v76, v199, v76
	v_mul_f32_e32 v77, v199, v77
	v_mul_f32_e32 v70, v199, v70
	v_mul_f32_e32 v71, v199, v71
	v_mul_f32_e32 v72, v199, v72
	v_mul_f32_e32 v73, v199, v73
	v_mul_f32_e32 v66, v199, v66
	v_mul_f32_e32 v67, v199, v67
	v_mul_f32_e32 v68, v199, v68
	v_mul_f32_e32 v69, v199, v69
	v_mul_f32_e32 v62, v200, v62
	v_mul_f32_e32 v63, v200, v63
	v_mul_f32_e32 v64, v200, v64
	v_mul_f32_e32 v65, v200, v65
	v_mul_f32_e32 v58, v200, v58
	v_mul_f32_e32 v59, v200, v59
	v_mul_f32_e32 v60, v200, v60
	v_mul_f32_e32 v61, v200, v61
	v_mul_f32_e32 v54, v200, v54
	v_mul_f32_e32 v55, v200, v55
	v_mul_f32_e32 v56, v200, v56
	v_mul_f32_e32 v57, v200, v57
	v_mul_f32_e32 v46, v200, v46
	v_mul_f32_e32 v47, v200, v47
	v_mul_f32_e32 v48, v200, v48
	v_mul_f32_e32 v49, v200, v49
	v_mul_f32_e32 v50, v201, v50
	v_mul_f32_e32 v51, v201, v51
	v_mul_f32_e32 v52, v201, v52
	v_mul_f32_e32 v53, v201, v53
	v_mul_f32_e32 v42, v201, v42
	v_mul_f32_e32 v43, v201, v43
	v_mul_f32_e32 v44, v201, v44
	v_mul_f32_e32 v45, v201, v45
	v_mul_f32_e32 v38, v201, v38
	v_mul_f32_e32 v39, v201, v39
	v_mul_f32_e32 v40, v201, v40
	v_mul_f32_e32 v41, v201, v41
	v_mul_f32_e32 v30, v201, v30
	v_mul_f32_e32 v31, v201, v31
	v_mul_f32_e32 v32, v201, v32
	v_mul_f32_e32 v33, v201, v33
	v_mul_f32_e32 v34, v202, v34
	v_mul_f32_e32 v35, v202, v35
	v_mul_f32_e32 v36, v202, v36
	v_mul_f32_e32 v37, v202, v37
	v_mul_f32_e32 v26, v202, v26
	v_mul_f32_e32 v27, v202, v27
	v_mul_f32_e32 v28, v202, v28
	v_mul_f32_e32 v29, v202, v29
	v_mul_f32_e32 v22, v202, v22
	v_mul_f32_e32 v23, v202, v23
	v_mul_f32_e32 v24, v202, v24
	v_mul_f32_e32 v25, v202, v25
	v_mul_f32_e32 v14, v202, v14
	v_mul_f32_e32 v15, v202, v15
	v_mul_f32_e32 v16, v202, v16
	v_mul_f32_e32 v17, v202, v17
	v_mul_f32_e32 v18, v203, v18
	v_mul_f32_e32 v19, v203, v19
	v_mul_f32_e32 v20, v203, v20
	v_mul_f32_e32 v21, v203, v21
	v_mul_f32_e32 v10, v203, v10
	v_mul_f32_e32 v11, v203, v11
	v_mul_f32_e32 v12, v203, v12
	v_mul_f32_e32 v13, v203, v13
	v_mul_f32_e32 v6, v203, v6
	v_mul_f32_e32 v7, v203, v7
	v_mul_f32_e32 v8, v203, v8
	v_mul_f32_e32 v9, v203, v9
	v_mul_f32_e32 v2, v203, v2
	v_mul_f32_e32 v3, v203, v3
	v_mul_f32_e32 v4, v203, v4
	v_mul_f32_e32 v5, v203, v5
	s_branch .Lp2r_hi_cont
.Lp2r_lo_cont:
	s_mul_hi_i32 s12, s14, 0xfe03f81
	s_lshr_b32 s13, s12, 31
	s_ashr_i32 s50, s12, 7
	s_add_i32 s50, s50, s13
	s_add_i32 s51, s50, 1
	s_mul_i32 s52, s51, 0x810
	s_mul_i32 s53, s50, 0xfffff7f0
	s_sub_i32 s54, 0, s52
	v_mov_b32_e32 v0, s54
	v_mov_b32_e32 v150, s53
	v_cmp_gt_i32_e32 vcc, s52, v190
	v_pk_mul_f32 v[148:149], v[120:121], v[124:125]
	v_pk_mul_f32 v[146:147], v[118:119], v[122:123]
	v_cndmask_b32_e32 v0, v0, v150, vcc
	v_mov_b64_e32 v[150:151], s[64:65]
	v_mov_b32_e32 v152, v1
	v_mov_b32_e32 v155, v1
	v_mov_b32_e32 v153, v1
	v_mov_b32_e32 v157, v1
	v_mov_b32_e32 v154, v1
	v_mov_b32_e32 v158, v1
	v_mov_b32_e32 v156, v1
	v_mov_b32_e32 v159, v1
	v_mad_i64_i32 v[150:151], s[12:13], v190, s33, v[150:151]
	v_add_u32_e32 v0, v0, v190
	v_mov_b32_dpp v152, v146 row_ror:1 row_mask:0xf bank_mask:0xf
	v_mov_b32_dpp v155, v146 row_ror:2 row_mask:0xf bank_mask:0xf
	v_mov_b32_dpp v153, v147 row_ror:1 row_mask:0xf bank_mask:0xf
	v_mov_b32_dpp v157, v147 row_ror:2 row_mask:0xf bank_mask:0xf
	v_mov_b32_dpp v154, v148 row_ror:1 row_mask:0xf bank_mask:0xf
	v_mov_b32_dpp v158, v148 row_ror:2 row_mask:0xf bank_mask:0xf
	v_mov_b32_dpp v156, v149 row_ror:1 row_mask:0xf bank_mask:0xf
	v_mov_b32_dpp v159, v149 row_ror:2 row_mask:0xf bank_mask:0xf
	v_lshl_add_u64 v[150:151], v[176:177], 1, v[150:151]
	s_and_saveexec_b64 s[14:15], s[4:5]
	s_cbranch_execz .LBB0_167
	v_cmp_gt_i32_e64 s[12:13], 2, v0
	s_nop 1
	v_cndmask_b32_e64 v160, v155, 0, s[12:13]
	v_cndmask_b32_e64 v161, v157, 0, s[12:13]
	v_cndmask_b32_e64 v158, v158, 0, s[12:13]
	v_cndmask_b32_e64 v159, v159, 0, s[12:13]
	v_cmp_eq_u32_e64 s[12:13], 0, v0
	s_waitcnt vmcnt(0)
	v_pk_mul_f32 v[158:159], v[136:137], v[158:159]
	v_cndmask_b32_e64 v152, v152, 0, s[12:13]
	v_cndmask_b32_e64 v153, v153, 0, s[12:13]
	v_cndmask_b32_e64 v155, v156, 0, s[12:13]
	v_pk_mul_f32 v[156:157], v[134:135], v[160:161]
	v_cndmask_b32_e64 v154, v154, 0, s[12:13]
	v_pk_fma_f32 v[152:153], v[142:143], v[152:153], v[156:157]
	v_pk_fma_f32 v[154:155], v[144:145], v[154:155], v[158:159]
	v_pk_fma_f32 v[152:153], v[146:147], v[138:139], v[152:153]
	v_pk_fma_f32 v[154:155], v[148:149], v[140:141], v[154:155]
	v_pk_mul_f32 v[152:153], v[126:127], v[152:153]
	v_pk_mul_f32 v[154:155], v[128:129], v[154:155]
	v_cvt_pk_bf16_f32 v152, v152, v153
	s_nop 0
	v_cvt_pk_bf16_f32 v153, v154, v155
	global_store_dwordx2 v[150:151], v[152:153], off

; __device__ __forceinline__ unsigned cvt_pk_bf16(float lo, float hi) { unsigned r; asm volatile("v_cvt_pk_bf16_f32 %0, %1, %2" : "=v"(r) : "v"(lo), "v"(hi)); return r; }
;     __device__ __forceinline__ void operator()(const f32x4 (&acc)[2][2][4][2], const Unit& u, int wr, int wc, int fr, int fq) const {
;     ...
;         if (u.pn >= 16) {
;             const int col0 = u.pn * BM + wc * 32 + 8 * fq;
;             f32x4 bv[2][2];
; #pragma unroll
;             for (int bj = 0; bj < 2; ++bj)
; #pragma unroll
;                 for (int n = 0; n < 2; ++n) bv[bj][n] = *(const f32x4*)(bias + col0 + bj * HALF + 4 * n);
; #pragma unroll
;             for (int ai = 0; ai < 2; ++ai)
; #pragma unroll
;                 for (int m = 0; m < 4; ++m) { bf16_t* rowp = O + (size_t)(rbase + ai * HALF + m * 16) * DP + (col0 - 2048);
; #pragma unroll
;                     for (int bj = 0; bj < 2; ++bj) { const f32x4 v0 = acc[ai][bj][m][0] + bv[bj][0], v1 = acc[ai][bj][m][1] + bv[bj][1];
;                         u32x4 w; w.x = cvt_pk_bf16(v0[0], v0[1]); w.y = cvt_pk_bf16(v0[2], v0[3]); w.z = cvt_pk_bf16(v1[0], v1[1]); w.w = cvt_pk_bf16(v1[2], v1[3]);
;                         *(u32x4*)(rowp + bj * HALF) = w; } }
.Lp2r_hi_cont:
	v_mov_b64_e32 v[146:147], s[64:65]
	v_mad_i64_i32 v[148:149], s[12:13], v190, s33, v[146:147]
	v_lshlrev_b32_e32 v0, 1, v0
	v_lshl_add_u64 v[148:149], v[148:149], 0, v[0:1]
	s_waitcnt vmcnt(0)
	v_pk_add_f32 v[150:151], v[124:125], v[140:141]
	v_pk_add_f32 v[128:129], v[128:129], v[144:145]
	v_pk_add_f32 v[126:127], v[126:127], v[142:143]
	v_pk_add_f32 v[124:125], v[122:123], v[138:139]
	v_cvt_pk_bf16_f32 v122, v126, v127
	v_cvt_pk_bf16_f32 v123, v128, v129
	v_pk_add_f32 v[118:119], v[118:119], v[134:135]
	v_cvt_pk_bf16_f32 v124, v124, v125
	v_cvt_pk_bf16_f32 v125, v150, v151
	global_store_dwordx4 v[148:149], v[122:125], off offset:-4096
	v_pk_add_f32 v[120:121], v[120:121], v[136:137]
	v_pk_add_f32 v[112:113], v[112:113], v[144:145]
	v_pk_add_f32 v[122:123], v[116:117], v[132:133]
	v_pk_add_f32 v[116:117], v[114:115], v[130:131]
	v_cvt_pk_bf16_f32 v114, v118, v119
	v_cvt_pk_bf16_f32 v115, v120, v121
	v_pk_add_f32 v[110:111], v[110:111], v[142:143]
	v_cvt_pk_bf16_f32 v116, v116, v117
	v_cvt_pk_bf16_f32 v117, v122, v123
	global_store_dwordx4 v[148:149], v[114:117], off offset:-3840
	v_pk_add_f32 v[102:103], v[102:103], v[134:135]
	v_pk_add_f32 v[104:105], v[104:105], v[136:137]
	v_or_b32_e32 v114, 16, v190
	v_mad_i64_i32 v[114:115], s[12:13], v114, s33, v[146:147]
	v_lshl_add_u64 v[114:115], v[114:115], 0, v[0:1]
	v_pk_add_f32 v[116:117], v[108:109], v[140:141]
	v_pk_add_f32 v[108:109], v[106:107], v[138:139]
	v_cvt_pk_bf16_f32 v106, v110, v111
	v_cvt_pk_bf16_f32 v107, v112, v113
	v_pk_add_f32 v[96:97], v[96:97], v[144:145]
	v_cvt_pk_bf16_f32 v108, v108, v109
	v_cvt_pk_bf16_f32 v109, v116, v117
	global_store_dwordx4 v[114:115], v[106:109], off offset:-4096
	v_pk_add_f32 v[94:95], v[94:95], v[142:143]
	v_pk_add_f32 v[86:87], v[86:87], v[134:135]
	v_pk_add_f32 v[106:107], v[100:101], v[132:133]
	v_pk_add_f32 v[100:101], v[98:99], v[130:131]
	v_cvt_pk_bf16_f32 v98, v102, v103
	v_cvt_pk_bf16_f32 v99, v104, v105
	v_pk_add_f32 v[88:89], v[88:89], v[136:137]
	v_cvt_pk_bf16_f32 v100, v100, v101
	v_cvt_pk_bf16_f32 v101, v106, v107
	global_store_dwordx4 v[114:115], v[98:101], off offset:-3840
	v_pk_add_f32 v[80:81], v[80:81], v[144:145]
	v_pk_add_f32 v[78:79], v[78:79], v[142:143]
	v_or_b32_e32 v98, 32, v190
	v_mad_i64_i32 v[98:99], s[12:13], v98, s33, v[146:147]
	v_lshl_add_u64 v[98:99], v[98:99], 0, v[0:1]
	v_pk_add_f32 v[100:101], v[92:93], v[140:141]
	v_pk_add_f32 v[92:93], v[90:91], v[138:139]
	v_cvt_pk_bf16_f32 v90, v94, v95
	v_cvt_pk_bf16_f32 v91, v96, v97
	v_pk_add_f32 v[70:71], v[70:71], v[134:135]
	v_cvt_pk_bf16_f32 v92, v92, v93
	v_cvt_pk_bf16_f32 v93, v100, v101
	global_store_dwordx4 v[98:99], v[90:93], off offset:-4096
	v_pk_add_f32 v[72:73], v[72:73], v[136:137]
	v_pk_add_f32 v[64:65], v[64:65], v[144:145]
	v_pk_add_f32 v[90:91], v[84:85], v[132:133]
	v_pk_add_f32 v[84:85], v[82:83], v[130:131]
	v_cvt_pk_bf16_f32 v82, v86, v87
	v_cvt_pk_bf16_f32 v83, v88, v89
	v_pk_add_f32 v[62:63], v[62:63], v[142:143]
	v_cvt_pk_bf16_f32 v84, v84, v85
	v_cvt_pk_bf16_f32 v85, v90, v91
	global_store_dwordx4 v[98:99], v[82:85], off offset:-3840
	v_pk_add_f32 v[54:55], v[54:55], v[134:135]
	v_pk_add_f32 v[56:57], v[56:57], v[136:137]
	v_or_b32_e32 v82, 48, v190
	v_mad_i64_i32 v[82:83], s[12:13], v82, s33, v[146:147]
	v_lshl_add_u64 v[82:83], v[82:83], 0, v[0:1]
	v_pk_add_f32 v[84:85], v[76:77], v[140:141]
	v_pk_add_f32 v[76:77], v[74:75], v[138:139]
	v_cvt_pk_bf16_f32 v74, v78, v79
	v_cvt_pk_bf16_f32 v75, v80, v81
	v_pk_add_f32 v[50:51], v[50:51], v[142:143]
	v_cvt_pk_bf16_f32 v76, v76, v77
	v_cvt_pk_bf16_f32 v77, v84, v85
	global_store_dwordx4 v[82:83], v[74:77], off offset:-4096
	v_pk_add_f32 v[38:39], v[38:39], v[134:135]
; __device__ __forceinline__ unsigned cvt_pk_bf16(float lo, float hi) { unsigned r; asm volatile("v_cvt_pk_bf16_f32 %0, %1, %2" : "=v"(r) : "v"(lo), "v"(hi)); return r; }
;     __device__ __forceinline__ void operator()(const f32x4 (&acc)[2][2][4][2], const Unit& u, int wr, int wc, int fr, int fq) const {
;     ...
;                 for (int m = 0; m < 4; ++m) { bf16_t* rowp = O + (size_t)(rbase + ai * HALF + m * 16) * DP + (col0 - 2048);
; #pragma unroll
;                     for (int bj = 0; bj < 2; ++bj) { const f32x4 v0 = acc[ai][bj][m][0] + bv[bj][0], v1 = acc[ai][bj][m][1] + bv[bj][1];
;                         u32x4 w; w.x = cvt_pk_bf16(v0[0], v0[1]); w.y = cvt_pk_bf16(v0[2], v0[3]); w.z = cvt_pk_bf16(v1[0], v1[1]); w.w = cvt_pk_bf16(v1[2], v1[3]);
;                         *(u32x4*)(rowp + bj * HALF) = w; } }
	v_pk_add_f32 v[40:41], v[40:41], v[136:137]
	v_pk_add_f32 v[74:75], v[68:69], v[132:133]
	v_pk_add_f32 v[68:69], v[66:67], v[130:131]
	v_cvt_pk_bf16_f32 v66, v70, v71
	v_cvt_pk_bf16_f32 v67, v72, v73
	v_pk_add_f32 v[34:35], v[34:35], v[142:143]
	v_cvt_pk_bf16_f32 v68, v68, v69
	v_cvt_pk_bf16_f32 v69, v74, v75
	global_store_dwordx4 v[82:83], v[66:69], off offset:-3840
	v_pk_add_f32 v[22:23], v[22:23], v[134:135]
	v_pk_add_f32 v[24:25], v[24:25], v[136:137]
	v_add_u32_e32 v66, 0x80, v190
	v_mad_i64_i32 v[66:67], s[12:13], v66, s33, v[146:147]
	v_lshl_add_u64 v[66:67], v[66:67], 0, v[0:1]
	v_pk_add_f32 v[68:69], v[60:61], v[140:141]
	v_pk_add_f32 v[60:61], v[58:59], v[138:139]
	v_cvt_pk_bf16_f32 v58, v62, v63
	v_cvt_pk_bf16_f32 v59, v64, v65
	v_pk_add_f32 v[18:19], v[18:19], v[142:143]
	v_cvt_pk_bf16_f32 v60, v60, v61
	v_cvt_pk_bf16_f32 v61, v68, v69
	global_store_dwordx4 v[66:67], v[58:61], off offset:-4096
	v_pk_add_f32 v[8:9], v[8:9], v[136:137]
	v_pk_add_f32 v[6:7], v[6:7], v[134:135]
	v_pk_add_f32 v[58:59], v[48:49], v[132:133]
	v_pk_add_f32 v[48:49], v[46:47], v[130:131]
	v_cvt_pk_bf16_f32 v46, v54, v55
	v_cvt_pk_bf16_f32 v47, v56, v57
	s_nop 0
	v_cvt_pk_bf16_f32 v48, v48, v49
	v_cvt_pk_bf16_f32 v49, v58, v59
	global_store_dwordx4 v[66:67], v[46:49], off offset:-3840
	s_nop 1
	v_add_u32_e32 v46, 0x90, v190
	v_mad_i64_i32 v[46:47], s[12:13], v46, s33, v[146:147]
	v_lshl_add_u64 v[46:47], v[46:47], 0, v[0:1]
	v_pk_add_f32 v[48:49], v[52:53], v[144:145]
	v_pk_add_f32 v[52:53], v[44:45], v[140:141]
	v_pk_add_f32 v[44:45], v[42:43], v[138:139]
	v_cvt_pk_bf16_f32 v42, v50, v51
	v_cvt_pk_bf16_f32 v43, v48, v49
	s_nop 0
	v_cvt_pk_bf16_f32 v44, v44, v45
	v_cvt_pk_bf16_f32 v45, v52, v53
	global_store_dwordx4 v[46:47], v[42:45], off offset:-4096
	s_nop 1
	v_pk_add_f32 v[42:43], v[32:33], v[132:133]
	v_pk_add_f32 v[32:33], v[30:31], v[130:131]
	v_cvt_pk_bf16_f32 v30, v38, v39
	v_cvt_pk_bf16_f32 v31, v40, v41
	s_nop 0
	v_cvt_pk_bf16_f32 v32, v32, v33
	v_cvt_pk_bf16_f32 v33, v42, v43
	global_store_dwordx4 v[46:47], v[30:33], off offset:-3840
	s_nop 1
	v_add_u32_e32 v30, 0xa0, v190
	v_mad_i64_i32 v[30:31], s[12:13], v30, s33, v[146:147]
	v_lshl_add_u64 v[30:31], v[30:31], 0, v[0:1]
	v_pk_add_f32 v[32:33], v[36:37], v[144:145]
	v_pk_add_f32 v[36:37], v[28:29], v[140:141]
	v_pk_add_f32 v[28:29], v[26:27], v[138:139]
	v_cvt_pk_bf16_f32 v26, v34, v35
	v_cvt_pk_bf16_f32 v27, v32, v33
	s_nop 0
	v_cvt_pk_bf16_f32 v28, v28, v29
	v_cvt_pk_bf16_f32 v29, v36, v37
	global_store_dwordx4 v[30:31], v[26:29], off offset:-4096
	s_nop 1
	v_pk_add_f32 v[26:27], v[16:17], v[132:133]
	v_pk_add_f32 v[16:17], v[14:15], v[130:131]
	v_cvt_pk_bf16_f32 v14, v22, v23
	v_cvt_pk_bf16_f32 v15, v24, v25
	s_nop 0
	v_cvt_pk_bf16_f32 v16, v16, v17
	v_cvt_pk_bf16_f32 v17, v26, v27
	global_store_dwordx4 v[30:31], v[14:17], off offset:-3840
	s_nop 1
	v_add_u32_e32 v14, 0xb0, v190
	v_mad_i64_i32 v[14:15], s[12:13], v14, s33, v[146:147]
	v_lshl_add_u64 v[14:15], v[14:15], 0, v[0:1]
	v_pk_add_f32 v[16:17], v[20:21], v[144:145]
	v_pk_add_f32 v[20:21], v[12:13], v[140:141]
	v_pk_add_f32 v[12:13], v[10:11], v[138:139]
	v_cvt_pk_bf16_f32 v10, v18, v19
	v_cvt_pk_bf16_f32 v11, v16, v17
	s_nop 0
	v_cvt_pk_bf16_f32 v12, v12, v13
	v_cvt_pk_bf16_f32 v13, v20, v21
	global_store_dwordx4 v[14:15], v[10:13], off offset:-4096
	s_nop 1
	v_pk_add_f32 v[10:11], v[4:5], v[132:133]
	v_pk_add_f32 v[4:5], v[2:3], v[130:131]
	v_cvt_pk_bf16_f32 v2, v6, v7
	v_cvt_pk_bf16_f32 v3, v8, v9
	s_nop 0
	v_cvt_pk_bf16_f32 v4, v4, v5
	v_cvt_pk_bf16_f32 v5, v10, v11
	global_store_dwordx4 v[14:15], v[2:5], off offset:-3840
	s_cmp_eq_u32 s48, s46
	s_mov_b64 s[12:13], -1
	s_cbranch_scc1 .LBB0_153
	s_branch .LBB0_203

; __device__ __forceinline__ unsigned cvt_pk_bf16(float lo, float hi) { unsigned r; asm volatile("v_cvt_pk_bf16_f32 %0, %1, %2" : "=v"(r) : "v"(lo), "v"(hi)); return r; }
; __device__ __forceinline__ float bflo(unsigned w) { return __uint_as_float(w << 16); }
; __device__ __forceinline__ float bfhi(unsigned w) { return __uint_as_float(w & 0xffff0000u); }
; __device__ __forceinline__ void norm_phase(KP p, bool first, int nslab) {
;     ...
;         if (xaware) { if (it < 8) m = 2048 * xl + 256 * it + jl * 8 + wave; else { if (gw >= 256) break; m = 64 * 256 + gw; } }
;         else { m = gw + it * NGW; if (m >= M) break; }
;         f32x4 v[4]; float s = 0.f;
;         if (first) { const f32x4* xr = (const f32x4*)src_row(p, m) + lane;
; #pragma unroll
;             for (int j = 0; j < 4; ++j) v[j] = __builtin_nontemporal_load(xr + 64 * j); }
;         else { const u32x2* xr = (const u32x2*)(X + (size_t)m * D) + lane;
; #pragma unroll
;             for (int j = 0; j < 4; ++j) { const u32x2 w = __builtin_nontemporal_load(xr + 64 * j); v[j] = (f32x4){bflo(w.x), bfhi(w.x), bflo(w.y), bfhi(w.y)}; } }
;         const bool fold = (!first) && m >= 64 * 256;
;         if (fold) { const f32x4* sl = (const f32x4*)(p->ws + WS_SLAB) + (size_t)(m - 64 * 256) * (D / 4) + lane;
;             for (int q = 0; q < nslab; ++q) {
; #pragma unroll
;                 for (int j = 0; j < 4; ++j) v[j] += sl[(size_t)q * 256 * (D / 4) + 64 * j]; } }
;         if (first || fold) { u32x2* xo = (u32x2*)(X + (size_t)m * D) + lane;
; #pragma unroll
;             for (int j = 0; j < 4; ++j) { u32x2 w; w.x = cvt_pk_bf16(v[j][0], v[j][1]); w.y = cvt_pk_bf16(v[j][2], v[j][3]); xo[64 * j] = w; } }
; #pragma unroll
;         for (int j = 0; j < 4; ++j) s += (v[j][0] * v[j][0] + v[j][1] * v[j][1]) + (v[j][2] * v[j][2] + v[j][3] * v[j][3]);
;         const float rinv = rsqrtf(wave_sum(s) * (1.f / D) + EPS);
;         u32x2* o8 = (u32x2*)(XN + (size_t)m * D) + lane;
; #pragma unroll
;         for (int j = 0; j < 4; ++j) { u32x2 w; w.x = cvt_pk_bf16(v[j][0] * rinv, v[j][1] * rinv); w.y = cvt_pk_bf16(v[j][2] * rinv, v[j][3] * rinv); o8[64 * j] = w; }
.LBB0_790:
	s_or_b64 exec, exec, s[4:5]
	s_mov_b64 s[4:5], s[94:95]
	v_mov_b32_e32 v0, v209
	s_waitcnt lgkmcnt(0)
	s_barrier
	s_load_dwordx2 s[8:9], s[4:5], 0xe8
	v_and_b32_e32 v2, 63, v0
	v_readfirstlane_b32 s6, v0
	s_nop 3
	s_lshr_b32 s6, s6, 6
	s_waitcnt lgkmcnt(0)
	s_add_u32 s10, s8, 0x25c8000
	s_addc_u32 s11, s9, 0
	s_add_u32 s12, s8, 0x18c48000
	s_addc_u32 s13, s9, 0
	s_add_u32 s14, s8, 0x19068000
	s_addc_u32 s15, s9, 0
	s_cmpk_lt_u32 s2, 128
	s_cbranch_scc1 .Lnm_part2_p7
	s_cmpk_lt_u32 s2, 0xe0
	s_cbranch_scc1 .LBB0_807
	s_sub_i32 s16, s2, 0xe0
	s_lshl_b32 s16, s16, 3
	s_add_i32 s16, s16, s6
	s_add_i32 s18, s16, 0x4000
	s_lshl_b32 s19, s18, 2
	s_lshl_b32 s18, s18, 11
	s_add_u32 s10, s10, s18
	s_addc_u32 s11, s11, 0
	s_add_u32 s14, s14, s19
	s_addc_u32 s15, s15, 0
	v_lshlrev_b32_e32 v5, 3, v2
	v_lshlrev_b32_e32 v6, 4, v2
	global_load_dwordx2 v[18:19], v5, s[10:11]
	global_load_dwordx2 v[20:21], v5, s[10:11] offset:512
	global_load_dwordx2 v[22:23], v5, s[10:11] offset:1024
	global_load_dwordx2 v[24:25], v5, s[10:11] offset:1536
	s_lshl_b32 s18, s16, 12
	s_add_u32 s18, s8, s18
	s_addc_u32 s19, s9, 0
	s_add_u32 s18, s18, 0x1a3ac000
	s_addc_u32 s19, s19, 0
	global_load_dwordx4 v[32:35], v6, s[18:19]
	global_load_dwordx4 v[36:39], v6, s[18:19] offset:1024
	global_load_dwordx4 v[40:43], v6, s[18:19] offset:2048
	global_load_dwordx4 v[44:47], v6, s[18:19] offset:3072
	s_add_u32 s18, s18, 0x100000
	s_addc_u32 s19, s19, 0
	global_load_dwordx4 v[48:51], v6, s[18:19]
	global_load_dwordx4 v[52:55], v6, s[18:19] offset:1024
	global_load_dwordx4 v[56:59], v6, s[18:19] offset:2048
	global_load_dwordx4 v[60:63], v6, s[18:19] offset:3072
	s_add_u32 s18, s18, 0x100000
	s_addc_u32 s19, s19, 0
	global_load_dwordx4 v[64:67], v6, s[18:19]
	global_load_dwordx4 v[68:71], v6, s[18:19] offset:1024
	global_load_dwordx4 v[72:75], v6, s[18:19] offset:2048
	global_load_dwordx4 v[76:79], v6, s[18:19] offset:3072
	s_add_u32 s18, s18, 0x100000
	s_addc_u32 s19, s19, 0
	global_load_dwordx4 v[80:83], v6, s[18:19]
	global_load_dwordx4 v[84:87], v6, s[18:19] offset:1024
	global_load_dwordx4 v[88:91], v6, s[18:19] offset:2048
	global_load_dwordx4 v[92:95], v6, s[18:19] offset:3072
	s_add_u32 s18, s18, 0x100000
	s_addc_u32 s19, s19, 0
	s_waitcnt vmcnt(16)
	v_lshlrev_b32_e32 v224, 16, v18
	v_and_b32_e32 v225, 0xffff0000, v18
	v_lshlrev_b32_e32 v226, 16, v19
	v_and_b32_e32 v227, 0xffff0000, v19
	v_lshlrev_b32_e32 v228, 16, v20
	v_and_b32_e32 v229, 0xffff0000, v20
	v_lshlrev_b32_e32 v230, 16, v21
	v_and_b32_e32 v231, 0xffff0000, v21
	v_lshlrev_b32_e32 v232, 16, v22
	v_and_b32_e32 v233, 0xffff0000, v22
	v_lshlrev_b32_e32 v234, 16, v23
	v_and_b32_e32 v235, 0xffff0000, v23
	v_lshlrev_b32_e32 v236, 16, v24
	v_and_b32_e32 v237, 0xffff0000, v24
	v_lshlrev_b32_e32 v238, 16, v25
	v_and_b32_e32 v239, 0xffff0000, v25
	s_waitcnt vmcnt(12)
	v_add_f32_e32 v224, v224, v32
	v_add_f32_e32 v225, v225, v33
	v_add_f32_e32 v226, v226, v34
	v_add_f32_e32 v227, v227, v35
	v_add_f32_e32 v228, v228, v36
	v_add_f32_e32 v229, v229, v37
	v_add_f32_e32 v230, v230, v38
	v_add_f32_e32 v231, v231, v39
	v_add_f32_e32 v232, v232, v40
	v_add_f32_e32 v233, v233, v41
	v_add_f32_e32 v234, v234, v42
	v_add_f32_e32 v235, v235, v43
	v_add_f32_e32 v236, v236, v44
	v_add_f32_e32 v237, v237, v45
	v_add_f32_e32 v238, v238, v46
	v_add_f32_e32 v239, v239, v47
	s_waitcnt vmcnt(8)
	v_add_f32_e32 v224, v224, v48
	v_add_f32_e32 v225, v225, v49
	v_add_f32_e32 v226, v226, v50
	v_add_f32_e32 v227, v227, v51
	v_add_f32_e32 v228, v228, v52
	v_add_f32_e32 v229, v229, v53
	v_add_f32_e32 v230, v230, v54
	v_add_f32_e32 v231, v231, v55
	v_add_f32_e32 v232, v232, v56
	v_add_f32_e32 v233, v233, v57
	v_add_f32_e32 v234, v234, v58
	v_add_f32_e32 v235, v235, v59
	v_add_f32_e32 v236, v236, v60
	v_add_f32_e32 v237, v237, v61
	v_add_f32_e32 v238, v238, v62
	v_add_f32_e32 v239, v239, v63
	s_waitcnt vmcnt(4)
	v_add_f32_e32 v224, v224, v64
	v_add_f32_e32 v225, v225, v65
	v_add_f32_e32 v226, v226, v66
	v_add_f32_e32 v227, v227, v67
	v_add_f32_e32 v228, v228, v68
	v_add_f32_e32 v229, v229, v69
	v_add_f32_e32 v230, v230, v70
	v_add_f32_e32 v231, v231, v71
	v_add_f32_e32 v232, v232, v72
	v_add_f32_e32 v233, v233, v73
	v_add_f32_e32 v234, v234, v74
	v_add_f32_e32 v235, v235, v75
	v_add_f32_e32 v236, v236, v76
	v_add_f32_e32 v237, v237, v77
	v_add_f32_e32 v238, v238, v78
	v_add_f32_e32 v239, v239, v79
	s_waitcnt vmcnt(0)
	v_add_f32_e32 v224, v224, v80
	v_add_f32_e32 v225, v225, v81
	v_add_f32_e32 v226, v226, v82
	v_add_f32_e32 v227, v227, v83
	v_add_f32_e32 v228, v228, v84
	v_add_f32_e32 v229, v229, v85
	v_add_f32_e32 v230, v230, v86
	v_add_f32_e32 v231, v231, v87
	v_add_f32_e32 v232, v232, v88
	v_add_f32_e32 v233, v233, v89
	v_add_f32_e32 v234, v234, v90
	v_add_f32_e32 v235, v235, v91
	v_add_f32_e32 v236, v236, v92
	v_add_f32_e32 v237, v237, v93
	v_add_f32_e32 v238, v238, v94
	v_add_f32_e32 v239, v239, v95
	v_cvt_pk_bf16_f32 v26, v224, v225
	v_cvt_pk_bf16_f32 v27, v226, v227
	global_store_dwordx2 v5, v[26:27], s[10:11] sc0 sc1
	v_cvt_pk_bf16_f32 v28, v228, v229
	v_cvt_pk_bf16_f32 v29, v230, v231
	global_store_dwordx2 v5, v[28:29], s[10:11] offset:512 sc0 sc1
	v_cvt_pk_bf16_f32 v30, v232, v233
	v_cvt_pk_bf16_f32 v31, v234, v235
	global_store_dwordx2 v5, v[30:31], s[10:11] offset:1024 sc0 sc1
	v_cvt_pk_bf16_f32 v32, v236, v237
	v_cvt_pk_bf16_f32 v33, v238, v239
	global_store_dwordx2 v5, v[32:33], s[10:11] offset:1536 sc0 sc1
	v_mul_f32_e32 v7, v224, v224
	v_fmac_f32_e32 v7, v225, v225
	v_fmac_f32_e32 v7, v226, v226
	v_fmac_f32_e32 v7, v227, v227
	v_fmac_f32_e32 v7, v228, v228
	v_fmac_f32_e32 v7, v229, v229
	v_fmac_f32_e32 v7, v230, v230
	v_fmac_f32_e32 v7, v231, v231
	v_fmac_f32_e32 v7, v232, v232
	v_fmac_f32_e32 v7, v233, v233
	v_fmac_f32_e32 v7, v234, v234
	v_fmac_f32_e32 v7, v235, v235
	v_fmac_f32_e32 v7, v236, v236
	v_fmac_f32_e32 v7, v237, v237
	v_fmac_f32_e32 v7, v238, v238
	v_fmac_f32_e32 v7, v239, v239
	v_xor_b32_e32 v10, 1, v2
	v_lshlrev_b32_e32 v10, 2, v10
	ds_bpermute_b32 v10, v10, v7
	s_waitcnt lgkmcnt(0)
	v_add_f32_e32 v7, v7, v10
	v_xor_b32_e32 v10, 2, v2
	v_lshlrev_b32_e32 v10, 2, v10
	ds_bpermute_b32 v10, v10, v7
	s_waitcnt lgkmcnt(0)
	v_add_f32_e32 v7, v7, v10
	v_xor_b32_e32 v10, 4, v2
	v_lshlrev_b32_e32 v10, 2, v10
	ds_bpermute_b32 v10, v10, v7
	s_waitcnt lgkmcnt(0)
	v_add_f32_e32 v7, v7, v10
	v_xor_b32_e32 v10, 8, v2
	v_lshlrev_b32_e32 v10, 2, v10
	ds_bpermute_b32 v10, v10, v7
	s_waitcnt lgkmcnt(0)
	v_add_f32_e32 v7, v7, v10
	v_xor_b32_e32 v10, 16, v2
	v_lshlrev_b32_e32 v10, 2, v10
	ds_bpermute_b32 v10, v10, v7
	s_waitcnt lgkmcnt(0)
	v_add_f32_e32 v7, v7, v10
	v_xor_b32_e32 v10, 32, v2
	v_lshlrev_b32_e32 v10, 2, v10
	ds_bpermute_b32 v10, v10, v7
	s_waitcnt lgkmcnt(0)
	v_add_f32_e32 v7, v7, v10
	v_fmamk_f32 v7, v7, 0x3a800000, v213
	v_rsq_f32_e32 v7, v7
	s_nop 0
	global_store_dword v1, v7, s[14:15] sc0 sc1
	s_branch .LBB0_807
